# attention units rebuild the LDS bias table only when the head changes (last head kept in v255 lane 60, reset per attention phase)
# speedup vs baseline: 1.0091x; 1.0091x over previous
; __device__ __forceinline__ int otid() { int t = threadIdx.x; asm volatile("" : "+v"(t)); return t; }
; #define PIN(i) karg_ptr(8 * (i))
; __global__ void __launch_bounds__(512, 2) fwd_megakernel(Params P) {
;     ...
;             float lam;
;             { const int lane = otid() & 63; const float* lq = PIN(I_LAMQ) + l * 128; const float* lk = PIN(I_LAMK) + l * 128;
;               const float a = wave_sum(lq[lane] * lk[lane]), b = wave_sum(lq[64 + lane] * lk[64 + lane]);
;               lam = expf(a) - expf(b) + (0.8f - 0.6f * expf(-0.3f * (float)l)); }
;             { const int lane_ = otid() & 63, gwv = bx * 8 + (otid() >> 6);
;               for (int tb = gwv; tb < MTOK / 16; tb += G * 8) att::pool_block(Zb, A2, tb * 16, lane_); }
;             __syncthreads();
;             for (int u = bx; u < 1024; u += G) {
.LBB0_279:
	s_or_b64 exec, exec, s[14:15]
	s_mov_b32 s6, -1
	v_writelane_b32 v255, s6, 60
	s_and_b64 vcc, exec, s[4:5]
	s_waitcnt lgkmcnt(0)
	s_barrier
	s_cbranch_vccnz .LBB0_348
	v_add_f32_e32 v2, v3, v27
	v_mul_f32_e32 v4, 0x3fb8aa3b, v2
	s_mov_b32 s4, 0x3fb8aa3b
	v_fma_f32 v5, v2, s4, -v4
	v_rndne_f32_e32 v6, v4
	v_fmac_f32_e32 v5, 0x32a5705f, v2
	v_sub_f32_e32 v4, v4, v6
	v_add_f32_e32 v4, v4, v5
	v_exp_f32_e32 v4, v4
	v_cvt_i32_f32_e32 v5, v6
	s_mov_b32 s5, 0xc2ce8ed0
	v_cmp_ngt_f32_e32 vcc, s5, v2
	s_mov_b32 s6, 0x42b17218
	v_ldexp_f32 v4, v4, v5
	v_add_f32_e32 v3, v26, v28
	v_cndmask_b32_e32 v4, 0, v4, vcc
	v_cmp_nlt_f32_e32 vcc, s6, v2
	v_readlane_b32 s8, v255, 49
	v_readlane_b32 s18, v255, 22
	v_cndmask_b32_e32 v2, v247, v4, vcc
	v_mul_f32_e32 v4, 0x3fb8aa3b, v3
	v_fma_f32 v5, v3, s4, -v4
	v_rndne_f32_e32 v6, v4
	v_fmac_f32_e32 v5, 0x32a5705f, v3
	v_sub_f32_e32 v4, v4, v6
	v_add_f32_e32 v4, v4, v5
	v_exp_f32_e32 v4, v4
	v_cvt_i32_f32_e32 v5, v6
	v_cmp_ngt_f32_e32 vcc, s5, v3
	s_mov_b32 s19, s2
	s_mov_b32 s20, s2
	v_ldexp_f32 v4, v4, v5
	v_cndmask_b32_e32 v4, 0, v4, vcc
	v_cmp_nlt_f32_e32 vcc, s6, v3
	s_mov_b32 s21, s2
	v_readlane_b32 s9, v255, 50
	v_cndmask_b32_e32 v3, v247, v4, vcc
	v_sub_f32_e32 v2, v2, v3
	v_cvt_f32_u32_e32 v3, s8
	v_mul_f32_e32 v3, 0xbe99999a, v3
	v_mul_f32_e32 v4, 0x3fb8aa3b, v3
	v_fma_f32 v5, v3, s4, -v4
	v_rndne_f32_e32 v6, v4
	v_fmac_f32_e32 v5, 0x32a5705f, v3
	v_sub_f32_e32 v4, v4, v6
	v_add_f32_e32 v4, v4, v5
	v_exp_f32_e32 v4, v4
	v_cvt_i32_f32_e32 v5, v6
	v_cmp_ngt_f32_e32 vcc, s5, v3
	v_ldexp_f32 v4, v4, v5
	s_nop 0
	v_cndmask_b32_e32 v4, 0, v4, vcc
	v_cmp_nlt_f32_e32 vcc, s6, v3
	s_nop 1
	v_cndmask_b32_e32 v3, v247, v4, vcc
	v_mov_b32_e32 v4, 0x3f4ccccd
	v_fmamk_f32 v3, v3, 0xbf19999a, v4
	v_add_f32_e32 v158, v3, v2
	s_branch .LBB0_283

; __device__ __forceinline__ void attn_unit(LAS unsigned char* lds, const bf16_t* Z, bf16_t* A2, const float* tabg, int seq_base, int S, int h, int qb, float lam) {
;     ...
;     for (int i = tid; i < 449; i += 512) { int d = i - 224; d = d < -128 ? -128 : (d > 128 ? 128 : d); tab[i] = tabg[h * 257 + d + 128]; }
; __global__ void __launch_bounds__(512, 2) fwd_megakernel(Params P) {
;     ...
;                 const int kind = u >> 9, v = u & 511, i = v >> 8, b = v & 255, xc = b & 7, j = b >> 3;
;                 if (kind == 0) att::attn_unit(lds, Zb, A2, tabg, 16384, 16384, xc >> 1, (xc & 1) * 64 + i * 32 + j, lam);
;                 else att::attn_unit(lds, Zb, A2, tabg, (xc >> 2) * 8192, 8192, xc & 3, i * 32 + j, lam);
.LBB0_283:
	s_and_b32 s24, s20, 7
	s_bfe_u32 s22, s21, 0x10008
	s_lshr_b32 s25, s21, 3
	s_bfe_u32 s23, s21, 0x50003
	s_and_b32 s26, s21, 7
	s_cmpk_gt_u32 s21, 0x1ff
	s_mov_b64 s[4:5], -1
	s_cbranch_scc0 .LBB0_316
	s_mov_b64 s[4:5], s[0:1]
	s_mov_b64 s[6:7], s[0:1]
	s_load_dwordx2 s[4:5], s[4:5], 0x98
	s_load_dwordx2 s[6:7], s[6:7], 0x90
	s_mov_b64 s[10:11], s[0:1]
	v_mov_b32_e32 v68, v0
	s_and_b32 s30, s21, 3
	s_nop 0
	v_readfirstlane_b32 s27, v68
	v_cmp_gt_i32_e32 vcc, s87, v68
	v_readlane_b32 s16, v255, 60
	s_mov_b64 s[8:9], exec
	s_cmp_eq_u32 s16, s30
	s_cbranch_scc1 .LBB0_292
	v_writelane_b32 v255, s30, 60
	s_and_saveexec_b64 s[8:9], vcc
	s_cbranch_execz .LBB0_292
	s_load_dwordx2 s[10:11], s[10:11], 0x98
	v_max_i32_e32 v2, 0xffffffc1, v68
	v_sub_u32_e32 v2, v2, v68
	v_add_u32_e32 v3, 0x1ff, v2
	s_mul_i32 s28, s30, 0x101
	v_cmp_lt_u32_e32 vcc, s86, v3
	s_mov_b64 s[16:17], -1
	v_mov_b32_e32 v2, v68
	s_and_saveexec_b64 s[14:15], vcc
	s_cbranch_execz .LBB0_289
	v_lshrrev_b32_e32 v2, 9, v3
	v_add_u32_e32 v4, 1, v2
	s_add_i32 s29, s28, 0xffffff20
	v_and_b32_e32 v5, 0xfffffe, v4
	v_add_u32_e32 v69, 0x200, v68
	s_mov_b32 s31, s29
	v_lshl_add_u32 v6, v68, 2, s93
	s_mov_b64 s[16:17], 0
	v_mov_b32_e32 v7, v5
	v_mov_b64_e32 v[2:3], v[68:69]

; __device__ __forceinline__ void attn_unit(LAS unsigned char* lds, const bf16_t* Z, bf16_t* A2, const float* tabg, int seq_base, int S, int h, int qb, float lam) {
;     ...
;     for (int i = tid; i < 449; i += 512) { int d = i - 224; d = d < -128 ? -128 : (d > 128 ? 128 : d); tab[i] = tabg[h * 257 + d + 128]; }
; __global__ void __launch_bounds__(512, 2) fwd_megakernel(Params P) {
;     ...
;                 const int kind = u >> 9, v = u & 511, i = v >> 8, b = v & 255, xc = b & 7, j = b >> 3;
;                 if (kind == 0) att::attn_unit(lds, Zb, A2, tabg, 16384, 16384, xc >> 1, (xc & 1) * 64 + i * 32 + j, lam);
;                 else att::attn_unit(lds, Zb, A2, tabg, (xc >> 2) * 8192, 8192, xc & 3, i * 32 + j, lam);
.LBB0_316:
	s_and_b64 vcc, exec, s[4:5]
	s_cbranch_vccz .LBB0_282
	s_mov_b64 s[4:5], s[0:1]
	s_mov_b64 s[6:7], s[0:1]
	s_load_dwordx2 s[4:5], s[4:5], 0x98
	s_load_dwordx2 s[6:7], s[6:7], 0x90
	s_mov_b64 s[10:11], s[0:1]
	v_mov_b32_e32 v68, v0
	s_lshr_b32 s28, s26, 1
	s_nop 0
	v_readfirstlane_b32 s26, v68
	v_cmp_gt_i32_e32 vcc, s87, v68
	v_readlane_b32 s16, v255, 60
	s_mov_b64 s[8:9], exec
	s_cmp_eq_u32 s16, s28
	s_cbranch_scc1 .LBB0_325
	v_writelane_b32 v255, s28, 60
	s_and_saveexec_b64 s[8:9], vcc
	s_cbranch_execz .LBB0_325
	s_load_dwordx2 s[10:11], s[10:11], 0x98
	v_max_i32_e32 v2, 0xffffffc1, v68
	v_sub_u32_e32 v2, v2, v68
	v_add_u32_e32 v3, 0x1ff, v2
	s_mul_i32 s27, s28, 0x101
	v_cmp_lt_u32_e32 vcc, s86, v3
	s_mov_b64 s[16:17], -1
	v_mov_b32_e32 v2, v68
	s_and_saveexec_b64 s[14:15], vcc
	s_cbranch_execz .LBB0_322
	v_lshrrev_b32_e32 v2, 9, v3
	v_add_u32_e32 v4, 1, v2
	s_add_i32 s29, s27, 0xffffff20
	v_and_b32_e32 v5, 0xfffffe, v4
	v_add_u32_e32 v69, 0x200, v68
	s_mov_b32 s30, s29
	v_lshl_add_u32 v6, v68, 2, s93
	s_mov_b64 s[16:17], 0
	v_mov_b32_e32 v7, v5
	v_mov_b64_e32 v[2:3], v[68:69]
